# adds: last XCD leader broadcasts the per-XCD release words itself (one poll+atomic hop less per grid barrier)
# speedup vs baseline: 1.0317x; 1.0051x over previous
.LBB0_357:
	s_or_b64 exec, exec, s[4:5]
	s_and_saveexec_b64 s[4:5], s[6:7]
	s_cbranch_execz .LBB0_359
	v_mov_b32_e32 v0, 1
	global_atomic_add v[2:3], v0, off
	v_add_co_u32_e32 v2, vcc, 0xffffef00, v2
	s_nop 1
	v_addc_co_u32_e32 v3, vcc, -1, v3, vcc
	global_atomic_add v[2:3], v0, off
	global_atomic_add v[2:3], v0, off offset:256
	global_atomic_add v[2:3], v0, off offset:512
	global_atomic_add v[2:3], v0, off offset:768
	global_atomic_add v[2:3], v0, off offset:1024
	global_atomic_add v[2:3], v0, off offset:1280
	global_atomic_add v[2:3], v0, off offset:1536
	global_atomic_add v[2:3], v0, off offset:1792
	global_atomic_add v[2:3], v0, off offset:2048
	global_atomic_add v[2:3], v0, off offset:2304
	global_atomic_add v[2:3], v0, off offset:2560
	global_atomic_add v[2:3], v0, off offset:2816
	global_atomic_add v[2:3], v0, off offset:3072
	global_atomic_add v[2:3], v0, off offset:3328
	global_atomic_add v[2:3], v0, off offset:3584
	global_atomic_add v[2:3], v0, off offset:3840
.LBB0_359:
	s_or_b64 exec, exec, s[4:5]
	s_mov_b64 s[4:5], exec
	v_mbcnt_lo_u32_b32 v0, s4, 0
	v_mbcnt_hi_u32_b32 v0, s5, v0
	v_cmp_eq_u32_e32 vcc, 0, v0
	s_waitcnt vmcnt(0)
	s_and_saveexec_b64 s[6:7], vcc
	s_cbranch_execz .LBB0_361
	s_bcnt1_i32_b64 s4, s[4:5]
	v_mov_b32_e32 v0, s4
	v_readlane_b32 s4, v254, 16
	v_readlane_b32 s5, v254, 17
	s_nop 4
.LBB0_361:
	s_or_b64 exec, exec, s[6:7]
	s_waitcnt vmcnt(0)

.LBB0_434:
	s_or_b64 exec, exec, s[4:5]
	s_mov_b64 s[4:5], exec
	v_mbcnt_lo_u32_b32 v0, s4, 0
	v_mbcnt_hi_u32_b32 v0, s5, v0
	v_cmp_eq_u32_e32 vcc, 0, v0
	s_waitcnt vmcnt(0)
	s_and_saveexec_b64 s[6:7], vcc
	s_cbranch_execz .LBB0_436
	s_bcnt1_i32_b64 s4, s[4:5]
	v_mov_b32_e32 v0, s4
	v_readlane_b32 s4, v254, 16
	v_readlane_b32 s5, v254, 17
	s_nop 4
.LBB0_436:
	s_or_b64 exec, exec, s[6:7]
	s_waitcnt vmcnt(0)

.LBB0_522:
	s_or_b64 exec, exec, s[4:5]
	s_mov_b64 s[4:5], exec
	v_mbcnt_lo_u32_b32 v0, s4, 0
	v_mbcnt_hi_u32_b32 v0, s5, v0
	v_cmp_eq_u32_e32 vcc, 0, v0
	s_waitcnt vmcnt(0)
	s_and_saveexec_b64 s[6:7], vcc
	s_cbranch_execz .LBB0_524
	s_bcnt1_i32_b64 s4, s[4:5]
	v_mov_b32_e32 v0, s4
	v_readlane_b32 s4, v254, 16
	v_readlane_b32 s5, v254, 17
	s_nop 4
.LBB0_524:
	s_or_b64 exec, exec, s[6:7]
	s_waitcnt vmcnt(0)

.LBB0_779:
	s_or_b64 exec, exec, s[4:5]
	s_mov_b64 s[4:5], exec
	v_mbcnt_lo_u32_b32 v0, s4, 0
	v_mbcnt_hi_u32_b32 v0, s5, v0
	v_cmp_eq_u32_e32 vcc, 0, v0
	s_waitcnt vmcnt(0)
	s_and_saveexec_b64 s[6:7], vcc
	s_cbranch_execz .LBB0_781
	s_bcnt1_i32_b64 s4, s[4:5]
	v_mov_b32_e32 v0, s4
	v_readlane_b32 s4, v254, 16
	v_readlane_b32 s5, v254, 17
	s_nop 4
.LBB0_781:
	s_or_b64 exec, exec, s[6:7]
	s_waitcnt vmcnt(0)

.LBB0_971:
	s_or_b64 exec, exec, s[4:5]
	s_mov_b64 s[4:5], exec
	v_mbcnt_lo_u32_b32 v0, s4, 0
	v_mbcnt_hi_u32_b32 v0, s5, v0
	v_cmp_eq_u32_e32 vcc, 0, v0
	s_waitcnt vmcnt(0)
	s_and_saveexec_b64 s[6:7], vcc
	s_cbranch_execz .LBB0_91
	s_bcnt1_i32_b64 s4, s[4:5]
	v_mov_b32_e32 v0, s4
	v_readlane_b32 s4, v254, 16
	v_readlane_b32 s5, v254, 17
	s_nop 4
	s_branch .LBB0_91
